# ffn activation row loop: plain (write-back) stores instead of sc1 write-through (the loop's counted waits for the next rows no longer wait for write-through acks)
# speedup vs baseline: 1.0052x; 1.0039x over previous
; __device__ __forceinline__ void store16_wt(void* p, u32x4 v) { asm volatile("global_store_dwordx4 %0, %1, off sc1\n\ts_nop 1" :: "v"(p), "v"(v) : "memory"); }
; __device__ __forceinline__ unsigned pk2(float lo, float hi) { f32x2_t v = {lo, hi}; bf16x2_t b = __builtin_convertvector(v, bf16x2_t); return __builtin_bit_cast(unsigned, b); }
; __device__ __forceinline__ float siluf(float x) { return x * __builtin_amdgcn_rcpf(1.0f + __expf(-x)); }
; __device__ __forceinline__ void unpack8(const u32x4 w, float* f) { f[0] = bflo(w.x); f[1] = bfhi(w.x); f[2] = bflo(w.y); f[3] = bfhi(w.y); f[4] = bflo(w.z); f[5] = bfhi(w.z); f[6] = bflo(w.w); f[7] = bfhi(w.w); }
; __device__ __forceinline__ void ffn_act_phase(const Ptrs& P, int l, int half, int gw, int NGW, int lane) {
;     ...
; #pragma unroll
;             for (int i = 0; i < 4; ++i) {
;                 if (meta && ((i0 + i) & 15) == 0) { g2 = (u32x4){0u, 0u, 0u, 0u}; g1 = g2; u2 = g2; u1 = g2; }
;                 float a2[8], a1[8], a0[8], c2[8], c1[8], c0[8], o[8];
;                 unpack8(g2, a2); unpack8(g1, a1); unpack8(gc[i], a0); unpack8(u2, c2); unpack8(u1, c1); unpack8(uc[i], c0);
; #pragma unroll
;                 for (int e = 0; e < 8; ++e) { const float gv = bg[e] + wg[0][e] * a2[e] + wg[1][e] * a1[e] + wg[2][e] * a0[e]; const float uv = bu[e] + wu[0][e] * c2[e] + wu[1][e] * c1[e] + wu[2][e] * c0[e]; o[e] = siluf(gv) * uv; }
;                 u32x4 wv; wv.x = pk2(o[0], o[1]); wv.y = pk2(o[2], o[3]); wv.z = pk2(o[4], o[5]); wv.w = pk2(o[6], o[7]);
;                 pg8::store16_wt(G2 + (size_t)(lr0 + i0 + i) * DFF + f0, wv);
.LBB0_1577:
	s_or_b64 exec, exec, s[12:13]
	v_lshlrev_b32_e32 v166, 16, v132
	v_and_b32_e32 v167, 0xffff0000, v132
	v_lshlrev_b32_e32 v168, 16, v140
	v_and_b32_e32 v169, 0xffff0000, v140
	v_pk_fma_f32 v[166:167], v[4:5], v[166:167], v[56:57]
	v_lshlrev_b32_e32 v162, 16, v144
	v_and_b32_e32 v163, 0xffff0000, v144
	v_pk_fma_f32 v[166:167], v[24:25], v[168:169], v[166:167]
	v_lshlrev_b32_e32 v170, 16, v128
	v_pk_fma_f32 v[166:167], v[40:41], v[162:163], v[166:167]
	v_and_b32_e32 v171, 0xffff0000, v128
	v_mul_f32_e32 v17, 0xbfb8aa3b, v166
	v_exp_f32_e32 v17, v17
	v_mul_f32_e32 v19, 0xbfb8aa3b, v167
	v_exp_f32_e32 v128, v19
	v_lshlrev_b32_e32 v172, 16, v136
	v_add_f32_e32 v17, 1.0, v17
	v_rcp_f32_e32 v174, v17
	v_add_f32_e32 v17, 1.0, v128
	v_rcp_f32_e32 v175, v17
	v_and_b32_e32 v173, 0xffff0000, v136
	v_pk_fma_f32 v[170:171], v[12:13], v[170:171], v[64:65]
	v_lshlrev_b32_e32 v18, 16, v124
	v_and_b32_e32 v19, 0xffff0000, v124
	v_pk_fma_f32 v[170:171], v[32:33], v[172:173], v[170:171]
	v_pk_mul_f32 v[166:167], v[166:167], v[174:175]
	v_pk_fma_f32 v[170:171], v[48:49], v[18:19], v[170:171]
	v_lshlrev_b32_e32 v174, 16, v141
	v_pk_mul_f32 v[166:167], v[170:171], v[166:167]
	v_lshlrev_b32_e32 v170, 16, v133
	v_and_b32_e32 v171, 0xffff0000, v133
	v_and_b32_e32 v175, 0xffff0000, v141
	v_lshlrev_b32_e32 v176, 16, v137
	v_and_b32_e32 v177, 0xffff0000, v137
	v_pk_fma_f32 v[136:137], v[6:7], v[170:171], v[58:59]
	v_lshlrev_b32_e32 v132, 16, v145
	v_and_b32_e32 v133, 0xffff0000, v145
	v_pk_fma_f32 v[136:137], v[26:27], v[174:175], v[136:137]
	v_lshlrev_b32_e32 v128, 16, v129
	v_pk_fma_f32 v[136:137], v[42:43], v[132:133], v[136:137]
	v_and_b32_e32 v129, 0xffff0000, v129
	v_mul_f32_e32 v17, 0xbfb8aa3b, v136
	v_exp_f32_e32 v17, v17
	v_mul_f32_e32 v140, 0xbfb8aa3b, v137
	v_exp_f32_e32 v141, v140
	v_pk_fma_f32 v[128:129], v[14:15], v[128:129], v[66:67]
	v_add_f32_e32 v17, 1.0, v17
	v_rcp_f32_e32 v140, v17
	v_add_f32_e32 v17, 1.0, v141
	v_rcp_f32_e32 v141, v17
	v_lshlrev_b32_e32 v124, 16, v125
	v_and_b32_e32 v125, 0xffff0000, v125
	v_pk_fma_f32 v[128:129], v[34:35], v[176:177], v[128:129]
	v_pk_mul_f32 v[136:137], v[136:137], v[140:141]
	v_lshlrev_b32_e32 v140, 16, v134
	v_and_b32_e32 v141, 0xffff0000, v134
	v_pk_fma_f32 v[128:129], v[50:51], v[124:125], v[128:129]
	v_lshlrev_b32_e32 v170, 16, v142
	v_and_b32_e32 v171, 0xffff0000, v142
	v_pk_fma_f32 v[140:141], v[0:1], v[140:141], v[52:53]
	v_pk_mul_f32 v[144:145], v[128:129], v[136:137]
	v_lshlrev_b32_e32 v136, 16, v146
	v_and_b32_e32 v137, 0xffff0000, v146
	v_pk_fma_f32 v[140:141], v[20:21], v[170:171], v[140:141]
	v_lshlrev_b32_e32 v178, 16, v130
	v_pk_fma_f32 v[140:141], v[36:37], v[136:137], v[140:141]
	v_and_b32_e32 v179, 0xffff0000, v130
	v_mul_f32_e32 v17, 0xbfb8aa3b, v140
	v_exp_f32_e32 v17, v17
	v_mul_f32_e32 v129, 0xbfb8aa3b, v141
	v_exp_f32_e32 v130, v129
	v_lshlrev_b32_e32 v180, 16, v138
	v_add_f32_e32 v17, 1.0, v17
	v_rcp_f32_e32 v182, v17
	v_add_f32_e32 v17, 1.0, v130
	v_rcp_f32_e32 v183, v17
	v_and_b32_e32 v181, 0xffff0000, v138
	v_pk_fma_f32 v[178:179], v[8:9], v[178:179], v[60:61]
	v_lshlrev_b32_e32 v128, 16, v126
	v_and_b32_e32 v129, 0xffff0000, v126
	v_pk_fma_f32 v[178:179], v[28:29], v[180:181], v[178:179]
	v_pk_mul_f32 v[140:141], v[140:141], v[182:183]
	v_pk_fma_f32 v[178:179], v[44:45], v[128:129], v[178:179]
	v_lshlrev_b32_e32 v182, 16, v135
	v_and_b32_e32 v183, 0xffff0000, v135
	v_pk_mul_f32 v[178:179], v[178:179], v[140:141]
	v_lshlrev_b32_e32 v184, 16, v143
	v_and_b32_e32 v185, 0xffff0000, v143
	v_lshlrev_b32_e32 v140, 16, v147
	v_and_b32_e32 v141, 0xffff0000, v147
	v_lshlrev_b32_e32 v146, 16, v139
	v_and_b32_e32 v147, 0xffff0000, v139
	v_pk_fma_f32 v[138:139], v[2:3], v[182:183], v[54:55]
	v_lshlrev_b32_e32 v134, 16, v127
	v_pk_fma_f32 v[138:139], v[22:23], v[184:185], v[138:139]
	v_and_b32_e32 v135, 0xffff0000, v127
	v_pk_fma_f32 v[138:139], v[38:39], v[140:141], v[138:139]
	v_lshlrev_b32_e32 v130, 16, v131
	v_mul_f32_e32 v17, 0xbfb8aa3b, v138
	v_exp_f32_e32 v17, v17
	v_mul_f32_e32 v126, 0xbfb8aa3b, v139
	v_exp_f32_e32 v142, v126
	v_and_b32_e32 v131, 0xffff0000, v131
	v_add_f32_e32 v17, 1.0, v17
	v_rcp_f32_e32 v126, v17
	v_add_f32_e32 v17, 1.0, v142
	v_rcp_f32_e32 v127, v17
	v_pk_fma_f32 v[130:131], v[10:11], v[130:131], v[62:63]
	v_cvt_pk_bf16_f32 v143, v144, v145
	v_pk_fma_f32 v[130:131], v[30:31], v[146:147], v[130:131]
	v_pk_mul_f32 v[126:127], v[138:139], v[126:127]
	v_pk_fma_f32 v[130:131], v[46:47], v[134:135], v[130:131]
	v_cvt_pk_bf16_f32 v144, v178, v179
	v_pk_mul_f32 v[126:127], v[130:131], v[126:127]
	v_cvt_pk_bf16_f32 v142, v166, v167
	v_cvt_pk_bf16_f32 v145, v126, v127
	v_pk_fma_f32 v[126:127], v[4:5], v[168:169], v[56:57]
	global_store_dwordx4 v[160:161], v[142:145], off
	s_nop 1
	v_lshlrev_b32_e32 v144, 16, v120
	v_and_b32_e32 v145, 0xffff0000, v120
	v_pk_fma_f32 v[126:127], v[24:25], v[162:163], v[126:127]
	v_pk_fma_f32 v[142:143], v[12:13], v[172:173], v[64:65]
	v_pk_fma_f32 v[126:127], v[40:41], v[144:145], v[126:127]
	v_lshlrev_b32_e32 v130, 16, v116
	v_mul_f32_e32 v17, 0xbfb8aa3b, v126
	v_exp_f32_e32 v17, v17
	v_mul_f32_e32 v120, 0xbfb8aa3b, v127
	v_exp_f32_e32 v120, v120
	v_and_b32_e32 v131, 0xffff0000, v116
	v_add_f32_e32 v17, 1.0, v17
	v_rcp_f32_e32 v138, v17
	v_add_f32_e32 v17, 1.0, v120
	v_rcp_f32_e32 v139, v17
	v_pk_fma_f32 v[142:143], v[32:33], v[18:19], v[142:143]
	v_pk_fma_f32 v[172:173], v[8:9], v[180:181], v[60:61]
	v_pk_fma_f32 v[142:143], v[48:49], v[130:131], v[142:143]
	v_pk_mul_f32 v[126:127], v[126:127], v[138:139]
	v_pk_fma_f32 v[172:173], v[28:29], v[128:129], v[172:173]
	v_pk_mul_f32 v[166:167], v[142:143], v[126:127]
	v_lshlrev_b32_e32 v142, 16, v121
; __device__ __forceinline__ void store16_wt(void* p, u32x4 v) { asm volatile("global_store_dwordx4 %0, %1, off sc1\n\ts_nop 1" :: "v"(p), "v"(v) : "memory"); }
; __device__ __forceinline__ unsigned pk2(float lo, float hi) { f32x2_t v = {lo, hi}; bf16x2_t b = __builtin_convertvector(v, bf16x2_t); return __builtin_bit_cast(unsigned, b); }
; __device__ __forceinline__ float siluf(float x) { return x * __builtin_amdgcn_rcpf(1.0f + __expf(-x)); }
; __device__ __forceinline__ void unpack8(const u32x4 w, float* f) { f[0] = bflo(w.x); f[1] = bfhi(w.x); f[2] = bflo(w.y); f[3] = bfhi(w.y); f[4] = bflo(w.z); f[5] = bfhi(w.z); f[6] = bflo(w.w); f[7] = bfhi(w.w); }
; __device__ __forceinline__ void ffn_act_phase(const Ptrs& P, int l, int half, int gw, int NGW, int lane) {
;     ...
; #pragma unroll
;             for (int i = 0; i < 4; ++i) {
;                 if (meta && ((i0 + i) & 15) == 0) { g2 = (u32x4){0u, 0u, 0u, 0u}; g1 = g2; u2 = g2; u1 = g2; }
;                 float a2[8], a1[8], a0[8], c2[8], c1[8], c0[8], o[8];
;                 unpack8(g2, a2); unpack8(g1, a1); unpack8(gc[i], a0); unpack8(u2, c2); unpack8(u1, c1); unpack8(uc[i], c0);
; #pragma unroll
;                 for (int e = 0; e < 8; ++e) { const float gv = bg[e] + wg[0][e] * a2[e] + wg[1][e] * a1[e] + wg[2][e] * a0[e]; const float uv = bu[e] + wu[0][e] * c2[e] + wu[1][e] * c1[e] + wu[2][e] * c0[e]; o[e] = siluf(gv) * uv; }
;                 u32x4 wv; wv.x = pk2(o[0], o[1]); wv.y = pk2(o[2], o[3]); wv.z = pk2(o[4], o[5]); wv.w = pk2(o[6], o[7]);
;                 pg8::store16_wt(G2 + (size_t)(lr0 + i0 + i) * DFF + f0, wv);
	v_and_b32_e32 v143, 0xffff0000, v121
	v_pk_fma_f32 v[120:121], v[6:7], v[174:175], v[58:59]
	v_lshlrev_b32_e32 v126, 16, v117
	v_pk_fma_f32 v[120:121], v[26:27], v[132:133], v[120:121]
	v_and_b32_e32 v127, 0xffff0000, v117
	v_pk_fma_f32 v[120:121], v[42:43], v[142:143], v[120:121]
	v_pk_fma_f32 v[146:147], v[10:11], v[146:147], v[62:63]
	v_mul_f32_e32 v17, 0xbfb8aa3b, v120
	v_exp_f32_e32 v17, v17
	v_mul_f32_e32 v116, 0xbfb8aa3b, v121
	v_exp_f32_e32 v138, v116
	v_pk_fma_f32 v[146:147], v[30:31], v[134:135], v[146:147]
	v_add_f32_e32 v17, 1.0, v17
	v_rcp_f32_e32 v116, v17
	v_add_f32_e32 v17, 1.0, v138
	v_rcp_f32_e32 v117, v17
	v_pk_fma_f32 v[138:139], v[14:15], v[176:177], v[66:67]
	s_mov_b64 s[12:13], 0x2c00
	v_pk_fma_f32 v[138:139], v[34:35], v[124:125], v[138:139]
	v_pk_mul_f32 v[116:117], v[120:121], v[116:117]
	v_pk_fma_f32 v[138:139], v[50:51], v[126:127], v[138:139]
	v_lshlrev_b32_e32 v120, 16, v118
	v_pk_mul_f32 v[168:169], v[138:139], v[116:117]
	v_pk_fma_f32 v[116:117], v[0:1], v[170:171], v[52:53]
	v_lshlrev_b32_e32 v138, 16, v122
	v_and_b32_e32 v139, 0xffff0000, v122
	v_pk_fma_f32 v[116:117], v[20:21], v[136:137], v[116:117]
	v_cvt_pk_bf16_f32 v166, v166, v167
	v_pk_fma_f32 v[116:117], v[36:37], v[138:139], v[116:117]
	v_cvt_pk_bf16_f32 v167, v168, v169
	v_mul_f32_e32 v17, 0xbfb8aa3b, v116
	v_exp_f32_e32 v17, v17
	v_mul_f32_e32 v121, 0xbfb8aa3b, v117
	v_exp_f32_e32 v122, v121
	v_and_b32_e32 v121, 0xffff0000, v118
	v_add_f32_e32 v17, 1.0, v17
	v_rcp_f32_e32 v170, v17
	v_add_f32_e32 v17, 1.0, v122
	v_rcp_f32_e32 v171, v17
	v_pk_fma_f32 v[172:173], v[44:45], v[120:121], v[172:173]
	v_lshlrev_b32_e32 v122, 16, v123
	v_and_b32_e32 v123, 0xffff0000, v123
	v_pk_mul_f32 v[116:117], v[116:117], v[170:171]
	v_pk_fma_f32 v[162:163], v[4:5], v[162:163], v[56:57]
	v_pk_mul_f32 v[170:171], v[172:173], v[116:117]
	v_pk_fma_f32 v[172:173], v[2:3], v[184:185], v[54:55]
	v_lshlrev_b32_e32 v116, 16, v119
	v_pk_fma_f32 v[172:173], v[22:23], v[140:141], v[172:173]
	v_cvt_pk_bf16_f32 v168, v170, v171
	v_pk_fma_f32 v[172:173], v[38:39], v[122:123], v[172:173]
	v_pk_fma_f32 v[162:163], v[24:25], v[144:145], v[162:163]
	v_mul_f32_e32 v17, 0xbfb8aa3b, v172
	v_exp_f32_e32 v17, v17
	v_mul_f32_e32 v117, 0xbfb8aa3b, v173
	v_exp_f32_e32 v165, v117
	v_and_b32_e32 v117, 0xffff0000, v119
	v_add_f32_e32 v17, 1.0, v17
	v_rcp_f32_e32 v118, v17
	v_add_f32_e32 v17, 1.0, v165
	v_rcp_f32_e32 v119, v17
	v_pk_fma_f32 v[146:147], v[46:47], v[116:117], v[146:147]
	v_pk_fma_f32 v[18:19], v[12:13], v[18:19], v[64:65]
	v_pk_fma_f32 v[132:133], v[6:7], v[132:133], v[58:59]
	v_pk_mul_f32 v[118:119], v[172:173], v[118:119]
	v_pk_fma_f32 v[18:19], v[32:33], v[130:131], v[18:19]
	v_pk_mul_f32 v[118:119], v[146:147], v[118:119]
	v_lshlrev_b32_e32 v146, 16, v108
	v_cvt_pk_bf16_f32 v169, v118, v119
	v_lshl_add_u64 v[118:119], v[160:161], 0, s[12:13]
	global_store_dwordx4 v[118:119], v[166:169], off
	s_nop 1
	v_lshlrev_b32_e32 v118, 16, v100
	v_and_b32_e32 v119, 0xffff0000, v100
	v_pk_fma_f32 v[162:163], v[40:41], v[118:119], v[162:163]
	v_pk_fma_f32 v[132:133], v[26:27], v[142:143], v[132:133]
	v_mul_f32_e32 v17, 0xbfb8aa3b, v162
	v_exp_f32_e32 v17, v17
	v_mul_f32_e32 v147, 0xbfb8aa3b, v163
	v_exp_f32_e32 v165, v147
	v_and_b32_e32 v147, 0xffff0000, v108
	v_add_f32_e32 v17, 1.0, v17
	v_rcp_f32_e32 v166, v17
	v_add_f32_e32 v17, 1.0, v165
	v_rcp_f32_e32 v167, v17
	v_pk_fma_f32 v[18:19], v[48:49], v[146:147], v[18:19]
	v_pk_fma_f32 v[124:125], v[14:15], v[124:125], v[66:67]
	v_pk_fma_f32 v[128:129], v[8:9], v[128:129], v[60:61]
	v_pk_mul_f32 v[162:163], v[162:163], v[166:167]
	v_lshlrev_b32_e32 v166, 16, v109
	v_pk_mul_f32 v[18:19], v[18:19], v[162:163]
	v_lshlrev_b32_e32 v162, 16, v101
	v_and_b32_e32 v163, 0xffff0000, v101
	v_pk_fma_f32 v[132:133], v[42:43], v[162:163], v[132:133]
	v_and_b32_e32 v167, 0xffff0000, v109
	v_mul_f32_e32 v17, 0xbfb8aa3b, v132
	v_exp_f32_e32 v17, v17
	v_mul_f32_e32 v165, 0xbfb8aa3b, v133
	v_exp_f32_e32 v165, v165
	v_pk_fma_f32 v[124:125], v[34:35], v[126:127], v[124:125]
	v_add_f32_e32 v17, 1.0, v17
	v_rcp_f32_e32 v168, v17
	v_add_f32_e32 v17, 1.0, v165
	v_rcp_f32_e32 v169, v17
	v_pk_fma_f32 v[124:125], v[50:51], v[166:167], v[124:125]
	v_lshlrev_b32_e32 v170, 16, v110
	v_and_b32_e32 v171, 0xffff0000, v110
	v_pk_mul_f32 v[132:133], v[132:133], v[168:169]
	v_lshlrev_b32_e32 v168, 16, v102
	v_pk_mul_f32 v[124:125], v[124:125], v[132:133]
	v_pk_fma_f32 v[132:133], v[0:1], v[136:137], v[52:53]
	v_and_b32_e32 v169, 0xffff0000, v102
	v_pk_fma_f32 v[132:133], v[20:21], v[138:139], v[132:133]
	v_pk_fma_f32 v[128:129], v[28:29], v[120:121], v[128:129]
	v_pk_fma_f32 v[132:133], v[36:37], v[168:169], v[132:133]
	v_pk_fma_f32 v[128:129], v[44:45], v[170:171], v[128:129]
	v_mul_f32_e32 v17, 0xbfb8aa3b, v132
	v_exp_f32_e32 v17, v17
	v_mul_f32_e32 v136, 0xbfb8aa3b, v133
	v_exp_f32_e32 v137, v136
	v_pk_fma_f32 v[134:135], v[10:11], v[134:135], v[62:63]
	v_add_f32_e32 v17, 1.0, v17
	v_rcp_f32_e32 v136, v17
	v_add_f32_e32 v17, 1.0, v137
	v_rcp_f32_e32 v137, v17
	v_lshlrev_b32_e32 v172, 16, v111
	v_and_b32_e32 v173, 0xffff0000, v111
	v_pk_fma_f32 v[134:135], v[30:31], v[116:117], v[134:135]
	v_pk_mul_f32 v[132:133], v[132:133], v[136:137]
	v_lshlrev_b32_e32 v136, 16, v103
; __device__ __forceinline__ void store16_wt(void* p, u32x4 v) { asm volatile("global_store_dwordx4 %0, %1, off sc1\n\ts_nop 1" :: "v"(p), "v"(v) : "memory"); }
; __device__ __forceinline__ unsigned pk2(float lo, float hi) { f32x2_t v = {lo, hi}; bf16x2_t b = __builtin_convertvector(v, bf16x2_t); return __builtin_bit_cast(unsigned, b); }
; __device__ __forceinline__ float siluf(float x) { return x * __builtin_amdgcn_rcpf(1.0f + __expf(-x)); }
; __device__ __forceinline__ void unpack8(const u32x4 w, float* f) { f[0] = bflo(w.x); f[1] = bfhi(w.x); f[2] = bflo(w.y); f[3] = bfhi(w.y); f[4] = bflo(w.z); f[5] = bfhi(w.z); f[6] = bflo(w.w); f[7] = bfhi(w.w); }
; __device__ __forceinline__ void ffn_act_phase(const Ptrs& P, int l, int half, int gw, int NGW, int lane) {
;     ...
;         for (int i0 = 0; i0 < 32; i0 += 4) {
;             u32x4 gc[4], uc[4];
; #pragma unroll
;             for (int i = 0; i < 4; ++i) { gc[i] = gn[i]; uc[i] = un[i]; }
;             if (i0 + 4 < 32) {
; #pragma unroll
;                 for (int i = 0; i < 4; ++i) { gn[i] = *(const u32x4*)(A2 + (size_t)(lr0 + i0 + 4 + i) * 11264 + f0); un[i] = *(const u32x4*)(A2 + (size_t)(lr0 + i0 + 4 + i) * 11264 + DFF + f0); } }
; #pragma unroll
;             for (int i = 0; i < 4; ++i) {
;                 if (meta && ((i0 + i) & 15) == 0) { g2 = (u32x4){0u, 0u, 0u, 0u}; g1 = g2; u2 = g2; u1 = g2; }
;                 float a2[8], a1[8], a0[8], c2[8], c1[8], c0[8], o[8];
;                 unpack8(g2, a2); unpack8(g1, a1); unpack8(gc[i], a0); unpack8(u2, c2); unpack8(u1, c1); unpack8(uc[i], c0);
; #pragma unroll
;                 for (int e = 0; e < 8; ++e) { const float gv = bg[e] + wg[0][e] * a2[e] + wg[1][e] * a1[e] + wg[2][e] * a0[e]; const float uv = bu[e] + wu[0][e] * c2[e] + wu[1][e] * c1[e] + wu[2][e] * c0[e]; o[e] = siluf(gv) * uv; }
;                 u32x4 wv; wv.x = pk2(o[0], o[1]); wv.y = pk2(o[2], o[3]); wv.z = pk2(o[4], o[5]); wv.w = pk2(o[6], o[7]);
;                 pg8::store16_wt(G2 + (size_t)(lr0 + i0 + i) * DFF + f0, wv);
;                 g2 = g1; g1 = gc[i]; u2 = u1; u1 = uc[i];
;             }
	v_pk_mul_f32 v[128:129], v[128:129], v[132:133]
	v_pk_fma_f32 v[132:133], v[2:3], v[140:141], v[54:55]
	v_and_b32_e32 v137, 0xffff0000, v103
	v_pk_fma_f32 v[132:133], v[22:23], v[122:123], v[132:133]
	v_pk_fma_f32 v[134:135], v[46:47], v[172:173], v[134:135]
	v_pk_fma_f32 v[132:133], v[38:39], v[136:137], v[132:133]
	v_pk_fma_f32 v[126:127], v[14:15], v[126:127], v[66:67]
	v_mul_f32_e32 v17, 0xbfb8aa3b, v132
	v_exp_f32_e32 v17, v17
	v_mul_f32_e32 v140, 0xbfb8aa3b, v133
	v_exp_f32_e32 v141, v140
	v_pk_fma_f32 v[126:127], v[34:35], v[166:167], v[126:127]
	v_add_f32_e32 v17, 1.0, v17
	v_rcp_f32_e32 v140, v17
	v_add_f32_e32 v17, 1.0, v141
	v_rcp_f32_e32 v141, v17
	v_pk_fma_f32 v[120:121], v[8:9], v[120:121], v[60:61]
	v_pk_fma_f32 v[122:123], v[2:3], v[122:123], v[54:55]
	v_pk_fma_f32 v[120:121], v[28:29], v[170:171], v[120:121]
	v_pk_mul_f32 v[132:133], v[132:133], v[140:141]
	v_pk_fma_f32 v[122:123], v[22:23], v[136:137], v[122:123]
	v_pk_mul_f32 v[140:141], v[134:135], v[132:133]
	v_cvt_pk_bf16_f32 v132, v18, v19
	v_cvt_pk_bf16_f32 v134, v128, v129
	v_lshl_add_u64 v[18:19], v[160:161], 0, s[94:95]
	v_pk_fma_f32 v[128:129], v[4:5], v[144:145], v[56:57]
	v_cvt_pk_bf16_f32 v133, v124, v125
	v_cvt_pk_bf16_f32 v135, v140, v141
	global_store_dwordx4 v[18:19], v[132:135], off
	s_nop 1
	v_lshlrev_b32_e32 v18, 16, v104
	v_and_b32_e32 v19, 0xffff0000, v104
	v_pk_fma_f32 v[118:119], v[24:25], v[118:119], v[128:129]
	v_pk_fma_f32 v[128:129], v[12:13], v[130:131], v[64:65]
	v_pk_fma_f32 v[18:19], v[40:41], v[18:19], v[118:119]
	v_lshlrev_b32_e32 v124, 16, v112
	v_mul_f32_e32 v17, 0xbfb8aa3b, v18
	v_exp_f32_e32 v17, v17
	v_mul_f32_e32 v118, 0xbfb8aa3b, v19
	v_exp_f32_e32 v119, v118
	v_and_b32_e32 v125, 0xffff0000, v112
	v_add_f32_e32 v17, 1.0, v17
	v_rcp_f32_e32 v118, v17
	v_add_f32_e32 v17, 1.0, v119
	v_rcp_f32_e32 v119, v17
	v_pk_fma_f32 v[128:129], v[32:33], v[146:147], v[128:129]
	v_pk_fma_f32 v[116:117], v[10:11], v[116:117], v[62:63]
	v_pk_fma_f32 v[124:125], v[48:49], v[124:125], v[128:129]
	v_pk_fma_f32 v[128:129], v[6:7], v[142:143], v[58:59]
	v_pk_mul_f32 v[18:19], v[18:19], v[118:119]
	v_lshlrev_b32_e32 v118, 16, v105
	v_and_b32_e32 v119, 0xffff0000, v105
	v_pk_fma_f32 v[128:129], v[26:27], v[162:163], v[128:129]
	v_pk_mul_f32 v[18:19], v[124:125], v[18:19]
	v_pk_fma_f32 v[118:119], v[42:43], v[118:119], v[128:129]
	v_lshlrev_b32_e32 v124, 16, v113
	v_mul_f32_e32 v17, 0xbfb8aa3b, v118
	v_exp_f32_e32 v17, v17
	v_mul_f32_e32 v125, 0xbfb8aa3b, v119
	v_exp_f32_e32 v129, v125
	v_and_b32_e32 v125, 0xffff0000, v113
	v_add_f32_e32 v17, 1.0, v17
	v_rcp_f32_e32 v128, v17
	v_add_f32_e32 v17, 1.0, v129
	v_rcp_f32_e32 v129, v17
	v_pk_fma_f32 v[124:125], v[50:51], v[124:125], v[126:127]
	v_lshlrev_b32_e32 v126, 16, v114
	v_pk_fma_f32 v[116:117], v[30:31], v[172:173], v[116:117]
	v_pk_mul_f32 v[118:119], v[118:119], v[128:129]
	v_pk_fma_f32 v[128:129], v[0:1], v[138:139], v[52:53]
	v_pk_mul_f32 v[118:119], v[124:125], v[118:119]
	v_lshlrev_b32_e32 v124, 16, v106
	v_and_b32_e32 v125, 0xffff0000, v106
	v_pk_fma_f32 v[128:129], v[20:21], v[168:169], v[128:129]
	s_mov_b64 s[12:13], 0x8400
	v_pk_fma_f32 v[124:125], v[36:37], v[124:125], v[128:129]
	s_waitcnt vmcnt(7)
	v_mov_b64_e32 v[146:147], v[86:87]
	v_mul_f32_e32 v17, 0xbfb8aa3b, v124
	v_exp_f32_e32 v17, v17
	v_mul_f32_e32 v127, 0xbfb8aa3b, v125
	v_exp_f32_e32 v129, v127
	v_and_b32_e32 v127, 0xffff0000, v114
	v_add_f32_e32 v17, 1.0, v17
	v_rcp_f32_e32 v128, v17
	v_add_f32_e32 v17, 1.0, v129
	v_rcp_f32_e32 v129, v17
	v_pk_fma_f32 v[120:121], v[44:45], v[126:127], v[120:121]
	v_lshlrev_b32_e32 v126, 16, v115
	v_and_b32_e32 v127, 0xffff0000, v115
	v_pk_mul_f32 v[124:125], v[124:125], v[128:129]
	v_pk_fma_f32 v[116:117], v[46:47], v[126:127], v[116:117]
	v_pk_mul_f32 v[120:121], v[120:121], v[124:125]
	v_lshlrev_b32_e32 v124, 16, v107
	v_and_b32_e32 v125, 0xffff0000, v107
	v_pk_fma_f32 v[122:123], v[38:39], v[124:125], v[122:123]
	v_mov_b64_e32 v[138:139], v[114:115]
	v_mul_f32_e32 v17, 0xbfb8aa3b, v122
	v_exp_f32_e32 v17, v17
	v_mul_f32_e32 v124, 0xbfb8aa3b, v123
	v_exp_f32_e32 v125, v124
	v_mov_b64_e32 v[130:131], v[110:111]
	v_add_f32_e32 v17, 1.0, v17
	v_rcp_f32_e32 v124, v17
	v_add_f32_e32 v17, 1.0, v125
	v_rcp_f32_e32 v125, v17
	v_mov_b64_e32 v[142:143], v[106:107]
	v_mov_b64_e32 v[134:135], v[102:103]
	s_add_i32 s17, s17, 4
	v_pk_mul_f32 v[122:123], v[122:123], v[124:125]
	s_waitcnt vmcnt(6)
	v_mov_b64_e32 v[126:127], v[90:91]
	v_pk_mul_f32 v[122:123], v[116:117], v[122:123]
	v_cvt_pk_bf16_f32 v116, v18, v19
	v_cvt_pk_bf16_f32 v117, v118, v119
	v_cvt_pk_bf16_f32 v118, v120, v121
	v_cvt_pk_bf16_f32 v119, v122, v123
	v_lshl_add_u64 v[18:19], v[160:161], 0, s[12:13]
	global_store_dwordx4 v[18:19], v[116:119], off
	s_nop 1
	s_mov_b64 s[12:13], 0xb000
	s_waitcnt vmcnt(4)
	v_mov_b64_e32 v[118:119], v[98:99]
	v_mov_b64_e32 v[122:123], v[94:95]
	v_lshl_add_u64 v[160:161], v[160:161], 0, s[12:13]
	s_and_b64 vcc, exec, s[84:85]
	v_mov_b64_e32 v[124:125], v[88:89]
	v_mov_b64_e32 v[116:117], v[96:97]
	v_mov_b64_e32 v[144:145], v[84:85]
	v_mov_b64_e32 v[120:121], v[92:93]
	v_mov_b64_e32 v[136:137], v[112:113]
	v_mov_b64_e32 v[128:129], v[108:109]
	v_mov_b64_e32 v[140:141], v[104:105]
	v_mov_b64_e32 v[132:133], v[100:101]
	s_cbranch_vccnz .LBB0_1573
